# P6 late entry 16us, P7 late entry 8us for odd WGs
# speedup vs baseline: 1.0079x; 1.0079x over previous
;     __device__ void init(int M, int N, int G_, int c_, unsigned long long mask_ = 0ull) { nM = M / BM; nN = mask_ ? __builtin_popcountll(mask_) : N / BM; nwg = nM * nN; G = G_; c = c_; mask = mask_; }
; #define LAUNDER() do { tid = threadIdx.x; asm volatile("" : "+v"(tid)); lane = tid & 63; wid = __builtin_amdgcn_readfirstlane(tid >> 6); bx = blockIdx.x; asm volatile("" : "+s"(bx)); \
;         vcu = (G % 8 == 0) ? (bx % 8) * (G / 8) + bx / 8 : bx; gw = vcu * 8 + wid; ws = P.ws; asm volatile("" : "+s"(ws)); Q.ws = ws; XB = (bf16_t*)(ws + WS_XB); } while (0)
; __global__ void __launch_bounds__(512, 2) trunk_fwd(Params P) {
;     ...
;         LAUNDER();
;         if (PH(12)) {   pg8::Gemm g{(const bf16_t*)(ws + WS_PB), (const bf16_t*)(ws + WS_WPLE), T, DM, PLE}; pg8::StaticOrder S; S.init(T, DM, G, bx);
;             Epi<EPI_MRG_A> E{}; E.O = (bf16_t*)(ws + WS_GP); E.ldc = DM;
;             pg8::gemm_phase(lds, g, S, E); }
.LBB0_672:
	s_or_b64 exec, exec, s[2:3]
	v_mov_b32_e32 v194, v160
	v_writelane_b32 v255, s13, 3
	s_waitcnt lgkmcnt(0)
	s_barrier
	v_readlane_b32 s30, v252, 50
	v_readfirstlane_b32 s0, v194
	s_nop 3
	s_bitcmp1_b32 s30, 0
	s_cbranch_scc0 .Lstagger_p7_done
	s_sleep 127
	s_sleep 127
.Lstagger_p7_done:
	s_nop 1
	v_writelane_b32 v255, s0, 4
	v_readlane_b32 s0, v254, 63
	v_readlane_b32 s1, v255, 0
	s_and_b64 vcc, exec, s[0:1]
	s_mov_b32 s0, s30
	s_cbranch_vccnz .LBB0_674
	s_ashr_i32 s0, s30, 31
	s_lshr_b32 s0, s0, 29
	s_add_i32 s0, s30, s0
	s_and_b32 s1, s0, -8
	s_sub_i32 s1, s30, s1
	v_readlane_b32 s2, v253, 63
	s_mul_i32 s1, s1, s2
	s_ashr_i32 s0, s0, 3
	s_add_i32 s0, s1, s0
